# half of the workgroups run the SSD chunk phase before attention (memory-bound and MFMA-bound phases overlap across CUs)
# speedup vs baseline: 1.0110x; 1.0110x over previous
; #define LAS __attribute__((address_space(3)))
; __device__ __forceinline__ int lbid() { int b = blockIdx.x; asm volatile("" : "+s"(b)); return b; }
; __device__ __forceinline__ int lgrid() { int g = gridDim.x; asm volatile("" : "+s"(g)); return g; }
; #define WSB() ((unsigned char*)in_ptr(26))
; __device__ __forceinline__ void ph_attn(LAS unsigned char* lds) {
;     const int G = lgrid(), bx = lbid();
;     unsigned char* ws = WSB();
;     const bf16_t* QN = (const bf16_t*)(ws + WS_QN); const bf16_t* QR = (const bf16_t*)(ws + WS_QR); const bf16_t* KN = (const bf16_t*)(ws + WS_KN);
;     const bf16_t* KR = (const bf16_t*)(ws + WS_KR); const bf16_t* VT = (const bf16_t*)(ws + WS_VT); bf16_t* ATT = (bf16_t*)(ws + WS_ATT);
;     for (int pi0 = bx; pi0 < NB * 64; pi0 += G) {
;         const int pi = (G % 8 == 0 && NB * 64 % 8 == 0 && pi0 - bx + G <= NB * 64) ? ((pi0 - bx) + (bx & 7) * (G >> 3) + (bx >> 3)) : pi0;
;         const int b = pi >> 6, h = (pi >> 3) & 7, j = pi & 7;
; #pragma unroll 1
;         for (int k = 0; k < 2; ++k) attn_unit(lds, QN, QR, KN, KR, VT, ATT, b, h, k ? j : 15 - j); }
;     __syncthreads();
; }
; __global__ void __launch_bounds__(512, 2) mega(Args a) {
;     ...
;         ph_attn(lds);
;         if (DUP_ATT) ph_attn(lds);
;     ...
;         ph_ssdc(lds);
;         if (DUP_SSDC) ph_ssdc(lds);
.LBB0_917:
	s_or_b64 exec, exec, s[4:5]
	s_bfe_u32 s95, s28, 0x10006
	s_cmp_eq_u32 s95, 0
	s_cbranch_scc0 .LBB0_954
.Lattn_head:
	s_mov_b32 s12, s50
	s_mov_b32 s13, s28
	s_waitcnt lgkmcnt(0)
	s_barrier
	s_movk_i32 s2, 0xd0
	s_cmpk_gt_i32 s13, 0xff
	s_cbranch_scc1 .LBB0_954
	s_ashr_i32 s5, s2, 31
	s_add_u32 s4, s0, s2
	s_addc_u32 s5, s1, s5
	s_load_dwordx2 s[8:9], s[4:5], 0x0
	s_mov_b32 s22, s13
	s_waitcnt lgkmcnt(0)
	s_add_u32 s14, s8, 0x17600000
	s_addc_u32 s15, s9, 0
	s_add_u32 s16, s8, 0x19600000
	s_addc_u32 s17, s9, 0
	s_add_u32 s4, s8, 0x1a600000
	s_addc_u32 s5, s9, 0
	s_add_u32 s6, s8, 0x7200000
	s_addc_u32 s7, s9, 0
	s_add_u32 s64, s8, 0x1c600000
	s_addc_u32 s65, s9, 0
	s_add_u32 s18, s8, 0x28600000
	s_addc_u32 s19, s9, 0
	s_and_b32 s2, s12, 7
	s_cmp_eq_u32 s2, 0
	s_cselect_b64 s[72:73], -1, 0
	s_and_b32 s2, s13, 7
	s_ashr_i32 s8, s12, 3
	s_mul_i32 s21, s2, s8
	s_ashr_i32 s2, s13, 3
	s_add_i32 s21, s21, s2
	s_branch .LBB0_920

; __device__ __forceinline__ void ph_attn(LAS unsigned char* lds) {
;     ...
;         for (int k = 0; k < 2; ++k) attn_unit(lds, QN, QR, KN, KR, VT, ATT, b, h, k ? j : 15 - j); }
;     __syncthreads();
; }
.LBB0_953:
	s_setprio 0
	v_readlane_b32 s36, v255, 0
	v_readlane_b32 s46, v255, 45
	v_readlane_b32 s44, v255, 47
	v_readlane_b32 s60, v255, 49
	v_readlane_b32 s28, v255, 2
	v_readlane_b32 s37, v255, 1
	v_readlane_b32 s47, v255, 46
	v_readlane_b32 s45, v255, 48
	v_readlane_b32 s61, v255, 50
	s_cmp_eq_u32 s95, 2
	s_cbranch_scc1 .LBB0_969

; __device__ __forceinline__ void ph_ssdc(LAS unsigned char* lds) {
;     ...
;     __syncthreads();
; __global__ void __launch_bounds__(512, 2) mega(Args a) {
;     ...
;         ph_attn(lds);
;         if (DUP_ATT) ph_attn(lds);
;     ...
;         ph_ssdc(lds);
;         if (DUP_SSDC) ph_ssdc(lds);
.LBB0_969:
	s_barrier
	s_cmp_eq_u32 s95, 1
	s_cbranch_scc0 .Lattn_ssdc_done
	s_mov_b32 s95, 2
	s_branch .Lattn_head
